# combined version with the ten GEMM main-loop heads aligned to 256 bytes
# speedup vs baseline: 1.0066x; 1.0066x over previous
;     __device__ bool next(int i, Unit& u) const { const long L = (long)i * G + c0; if (L >= n) return false; u.pm = (int)L / nN; u.pn = (int)L % nN; return true; }
; template <class Epi, class Sched, bool ALIGN_EPI = false, bool SP2 = false>
; __device__ __forceinline__ void gemm_phase(PG8_LAS unsigned char* lds, const Gemm g, const Sched& S, const Epi& E) {
;     ...
;     f32x4 acc[2][2][4][2];
; #pragma unroll
;     for (int a = 0; a < 2; ++a)
; #pragma unroll
;         for (int b = 0; b < 2; ++b)
; #pragma unroll
;             for (int m = 0; m < 4; ++m)
; #pragma unroll
;                 for (int n = 0; n < 2; ++n) acc[a][b][m][n] = (f32x4){0.f, 0.f, 0.f, 0.f};
;     ...
;         const bool has_next = S.next(ui + 1, nxt);
;         const char* nA = has_next ? (const char*)g.A + (size_t)nxt.pm * tstep : cA; const char* nB = has_next ? (const char*)g.Bt + (size_t)nxt.pn * tstep : cB;
;         for (int t = 0; t < nt; t += 2) {
;             const bool last = (t == nt - 2);
;             const char* a1 = cA + (size_t)(t + 1) * kstep;
;             const char* a2 = last ? nA : cA + (size_t)(t + 2) * kstep; const char* b2 = last ? nB : cB + (size_t)(t + 2) * kstep;
.LBB0_693:
	s_ashr_i32 s35, s34, 31
	s_lshl_b64 s[36:37], s[34:35], 19
	s_add_u32 s36, s27, s36
	s_addc_u32 s37, s29, s37
	s_and_b64 s[38:39], s[4:5], exec
	s_cselect_b32 s7, s37, s9
	s_cselect_b32 s35, s36, s8
	s_ashr_i32 s31, s30, 31
	s_lshl_b64 s[38:39], s[30:31], 19
	s_add_u32 s38, s33, s38
	s_addc_u32 s39, s42, s39
	s_and_b64 s[62:63], s[4:5], exec
	s_cselect_b32 s31, s39, s41
	s_cselect_b32 s61, s38, s40
	s_add_u32 s62, s40, 0x100
	v_mov_b32_e32 v0, 0
	s_addc_u32 s63, s41, 0
	s_mov_b32 s64, -2
	v_mov_b32_e32 v1, v0
	v_mov_b32_e32 v2, v0
	v_mov_b32_e32 v3, v0
	v_mov_b32_e32 v4, v0
	v_mov_b32_e32 v5, v0
	v_mov_b32_e32 v6, v0
	v_mov_b32_e32 v7, v0
	v_mov_b32_e32 v16, v0
	v_mov_b32_e32 v17, v0
	v_mov_b32_e32 v18, v0
	v_mov_b32_e32 v19, v0
	v_mov_b32_e32 v20, v0
	v_mov_b32_e32 v21, v0
	v_mov_b32_e32 v22, v0
	v_mov_b32_e32 v23, v0
	v_mov_b32_e32 v32, v0
	v_mov_b32_e32 v33, v0
	v_mov_b32_e32 v34, v0
	v_mov_b32_e32 v35, v0
	v_mov_b32_e32 v36, v0
	v_mov_b32_e32 v37, v0
	v_mov_b32_e32 v38, v0
	v_mov_b32_e32 v39, v0
	v_mov_b32_e32 v48, v0
	v_mov_b32_e32 v49, v0
	v_mov_b32_e32 v50, v0
	v_mov_b32_e32 v51, v0
	v_mov_b32_e32 v52, v0
	v_mov_b32_e32 v53, v0
	v_mov_b32_e32 v54, v0
	v_mov_b32_e32 v55, v0
	v_mov_b32_e32 v8, v0
	v_mov_b32_e32 v9, v0
	v_mov_b32_e32 v10, v0
	v_mov_b32_e32 v11, v0
	v_mov_b32_e32 v12, v0
	v_mov_b32_e32 v13, v0
	v_mov_b32_e32 v14, v0
	v_mov_b32_e32 v15, v0
	v_mov_b32_e32 v24, v0
	v_mov_b32_e32 v25, v0
	v_mov_b32_e32 v26, v0
	v_mov_b32_e32 v27, v0
	v_mov_b32_e32 v28, v0
	v_mov_b32_e32 v29, v0
	v_mov_b32_e32 v30, v0
	v_mov_b32_e32 v31, v0
	v_mov_b32_e32 v40, v0
	v_mov_b32_e32 v41, v0
	v_mov_b32_e32 v42, v0
	v_mov_b32_e32 v43, v0
	v_mov_b32_e32 v44, v0
	v_mov_b32_e32 v45, v0
	v_mov_b32_e32 v46, v0
	v_mov_b32_e32 v47, v0
	v_mov_b32_e32 v56, v0
	v_mov_b32_e32 v57, v0
	v_mov_b32_e32 v58, v0
	v_mov_b32_e32 v59, v0
	v_mov_b32_e32 v60, v0
	v_mov_b32_e32 v61, v0
	v_mov_b32_e32 v62, v0
	v_mov_b32_e32 v63, v0
	v_mov_b32_e32 v64, v0
	v_mov_b32_e32 v65, v0
	v_mov_b32_e32 v66, v0
	v_mov_b32_e32 v67, v0
	v_mov_b32_e32 v68, v0
	v_mov_b32_e32 v69, v0
	v_mov_b32_e32 v70, v0
	v_mov_b32_e32 v71, v0
	v_mov_b32_e32 v80, v0
	v_mov_b32_e32 v81, v0
	v_mov_b32_e32 v82, v0
	v_mov_b32_e32 v83, v0
	v_mov_b32_e32 v84, v0
	v_mov_b32_e32 v85, v0
	v_mov_b32_e32 v86, v0
	v_mov_b32_e32 v87, v0
	v_mov_b32_e32 v96, v0
	v_mov_b32_e32 v97, v0
	v_mov_b32_e32 v98, v0
	v_mov_b32_e32 v99, v0
	v_mov_b32_e32 v100, v0
	v_mov_b32_e32 v101, v0
	v_mov_b32_e32 v102, v0
	v_mov_b32_e32 v103, v0
	v_mov_b32_e32 v112, v0
	v_mov_b32_e32 v113, v0
	v_mov_b32_e32 v114, v0
	v_mov_b32_e32 v115, v0
	v_mov_b32_e32 v116, v0
	v_mov_b32_e32 v117, v0
	v_mov_b32_e32 v118, v0
	v_mov_b32_e32 v119, v0
	v_mov_b32_e32 v72, v0
	v_mov_b32_e32 v73, v0
	v_mov_b32_e32 v74, v0
	v_mov_b32_e32 v75, v0
	v_mov_b32_e32 v76, v0
	v_mov_b32_e32 v77, v0
	v_mov_b32_e32 v78, v0
	v_mov_b32_e32 v79, v0
	v_mov_b32_e32 v88, v0
	v_mov_b32_e32 v89, v0
	v_mov_b32_e32 v90, v0
	v_mov_b32_e32 v91, v0
	v_mov_b32_e32 v92, v0
	v_mov_b32_e32 v93, v0
	v_mov_b32_e32 v94, v0
	v_mov_b32_e32 v95, v0
	v_mov_b32_e32 v104, v0
	v_mov_b32_e32 v105, v0
	v_mov_b32_e32 v106, v0
	v_mov_b32_e32 v107, v0
	v_mov_b32_e32 v108, v0
	v_mov_b32_e32 v109, v0
	v_mov_b32_e32 v110, v0
	v_mov_b32_e32 v111, v0
	v_mov_b32_e32 v120, v0
	v_mov_b32_e32 v121, v0
	v_mov_b32_e32 v122, v0
	v_mov_b32_e32 v123, v0
	v_mov_b32_e32 v124, v0
	v_mov_b32_e32 v125, v0
	v_mov_b32_e32 v126, v0
	v_mov_b32_e32 v127, v0
	.p2alignl 8, 3212836864

;     __device__ bool next(int i, Unit& u) const { const long L = (long)i * G + c0; if (L >= n) return false; u.pm = (int)L / nN; u.pn = (int)L % nN; return true; }
; template <class Epi, class Sched, bool ALIGN_EPI = false, bool SP2 = false>
; __device__ __forceinline__ void gemm_phase(PG8_LAS unsigned char* lds, const Gemm g, const Sched& S, const Epi& E) {
;     ...
;     f32x4 acc[2][2][4][2];
; #pragma unroll
;     for (int a = 0; a < 2; ++a)
; #pragma unroll
;         for (int b = 0; b < 2; ++b)
; #pragma unroll
;             for (int m = 0; m < 4; ++m)
; #pragma unroll
;                 for (int n = 0; n < 2; ++n) acc[a][b][m][n] = (f32x4){0.f, 0.f, 0.f, 0.f};
;     ...
;         const bool has_next = S.next(ui + 1, nxt);
;         const char* nA = has_next ? (const char*)g.A + (size_t)nxt.pm * tstep : cA; const char* nB = has_next ? (const char*)g.Bt + (size_t)nxt.pn * tstep : cB;
;         for (int t = 0; t < nt; t += 2) {
;             const bool last = (t == nt - 2);
;             const char* a1 = cA + (size_t)(t + 1) * kstep;
;             const char* a2 = last ? nA : cA + (size_t)(t + 2) * kstep; const char* b2 = last ? nB : cB + (size_t)(t + 2) * kstep;
.LBB0_767:
	s_add_u32 s59, s34, 0x100
	s_addc_u32 s60, s35, 0
	s_add_u32 s34, s36, 0xb0080
	v_mov_b32_e32 v0, 0
	s_addc_u32 s35, s37, 0
	s_mov_b32 s36, -2
	s_waitcnt lgkmcnt(0)
	v_mov_b32_e32 v1, v0
	v_mov_b32_e32 v2, v0
	v_mov_b32_e32 v3, v0
	v_mov_b32_e32 v4, v0
	v_mov_b32_e32 v5, v0
	v_mov_b32_e32 v6, v0
	v_mov_b32_e32 v7, v0
	v_mov_b32_e32 v16, v0
	v_mov_b32_e32 v17, v0
	v_mov_b32_e32 v18, v0
	v_mov_b32_e32 v19, v0
	v_mov_b32_e32 v20, v0
	v_mov_b32_e32 v21, v0
	v_mov_b32_e32 v22, v0
	v_mov_b32_e32 v23, v0
	v_mov_b32_e32 v32, v0
	v_mov_b32_e32 v33, v0
	v_mov_b32_e32 v34, v0
	v_mov_b32_e32 v35, v0
	v_mov_b32_e32 v36, v0
	v_mov_b32_e32 v37, v0
	v_mov_b32_e32 v38, v0
	v_mov_b32_e32 v39, v0
	v_mov_b32_e32 v48, v0
	v_mov_b32_e32 v49, v0
	v_mov_b32_e32 v50, v0
	v_mov_b32_e32 v51, v0
	v_mov_b32_e32 v52, v0
	v_mov_b32_e32 v53, v0
	v_mov_b32_e32 v54, v0
	v_mov_b32_e32 v55, v0
	v_mov_b32_e32 v8, v0
	v_mov_b32_e32 v9, v0
	v_mov_b32_e32 v10, v0
	v_mov_b32_e32 v11, v0
	v_mov_b32_e32 v12, v0
	v_mov_b32_e32 v13, v0
	v_mov_b32_e32 v14, v0
	v_mov_b32_e32 v15, v0
	v_mov_b32_e32 v24, v0
	v_mov_b32_e32 v25, v0
	v_mov_b32_e32 v26, v0
	v_mov_b32_e32 v27, v0
	v_mov_b32_e32 v28, v0
	v_mov_b32_e32 v29, v0
	v_mov_b32_e32 v30, v0
	v_mov_b32_e32 v31, v0
	v_mov_b32_e32 v40, v0
	v_mov_b32_e32 v41, v0
	v_mov_b32_e32 v42, v0
	v_mov_b32_e32 v43, v0
	v_mov_b32_e32 v44, v0
	v_mov_b32_e32 v45, v0
	v_mov_b32_e32 v46, v0
	v_mov_b32_e32 v47, v0
	v_mov_b32_e32 v56, v0
	v_mov_b32_e32 v57, v0
	v_mov_b32_e32 v58, v0
	v_mov_b32_e32 v59, v0
	v_mov_b32_e32 v60, v0
	v_mov_b32_e32 v61, v0
	v_mov_b32_e32 v62, v0
	v_mov_b32_e32 v63, v0
	v_mov_b32_e32 v64, v0
	v_mov_b32_e32 v65, v0
	v_mov_b32_e32 v66, v0
	v_mov_b32_e32 v67, v0
	v_mov_b32_e32 v68, v0
	v_mov_b32_e32 v69, v0
	v_mov_b32_e32 v70, v0
	v_mov_b32_e32 v71, v0
	v_mov_b32_e32 v80, v0
	v_mov_b32_e32 v81, v0
	v_mov_b32_e32 v82, v0
	v_mov_b32_e32 v83, v0
	v_mov_b32_e32 v84, v0
	v_mov_b32_e32 v85, v0
	v_mov_b32_e32 v86, v0
	v_mov_b32_e32 v87, v0
	v_mov_b32_e32 v96, v0
	v_mov_b32_e32 v97, v0
	v_mov_b32_e32 v98, v0
	v_mov_b32_e32 v99, v0
	v_mov_b32_e32 v100, v0
	v_mov_b32_e32 v101, v0
	v_mov_b32_e32 v102, v0
	v_mov_b32_e32 v103, v0
	v_mov_b32_e32 v112, v0
	v_mov_b32_e32 v113, v0
	v_mov_b32_e32 v114, v0
	v_mov_b32_e32 v115, v0
	v_mov_b32_e32 v116, v0
	v_mov_b32_e32 v117, v0
	v_mov_b32_e32 v118, v0
	v_mov_b32_e32 v119, v0
	v_mov_b32_e32 v72, v0
	v_mov_b32_e32 v73, v0
	v_mov_b32_e32 v74, v0
	v_mov_b32_e32 v75, v0
	v_mov_b32_e32 v76, v0
	v_mov_b32_e32 v77, v0
	v_mov_b32_e32 v78, v0
	v_mov_b32_e32 v79, v0
	v_mov_b32_e32 v88, v0
	v_mov_b32_e32 v89, v0
	v_mov_b32_e32 v90, v0
	v_mov_b32_e32 v91, v0
	v_mov_b32_e32 v92, v0
	v_mov_b32_e32 v93, v0
	v_mov_b32_e32 v94, v0
	v_mov_b32_e32 v95, v0
	v_mov_b32_e32 v104, v0
	v_mov_b32_e32 v105, v0
	v_mov_b32_e32 v106, v0
	v_mov_b32_e32 v107, v0
	v_mov_b32_e32 v108, v0
	v_mov_b32_e32 v109, v0
	v_mov_b32_e32 v110, v0
	v_mov_b32_e32 v111, v0
	v_mov_b32_e32 v120, v0
	v_mov_b32_e32 v121, v0
	v_mov_b32_e32 v122, v0
	v_mov_b32_e32 v123, v0
	v_mov_b32_e32 v124, v0
	v_mov_b32_e32 v125, v0
	v_mov_b32_e32 v126, v0
	v_mov_b32_e32 v127, v0
	.p2alignl 8, 3212836864

;     __device__ bool next(int i, Unit& u) const { const long L = (long)i * G + c0; if (L >= n) return false; u.pm = (int)L / nN; u.pn = (int)L % nN; return true; }
; template <class Epi, class Sched, bool ALIGN_EPI = false, bool SP2 = false>
; __device__ __forceinline__ void gemm_phase(PG8_LAS unsigned char* lds, const Gemm g, const Sched& S, const Epi& E) {
;     ...
;     f32x4 acc[2][2][4][2];
; #pragma unroll
;     for (int a = 0; a < 2; ++a)
; #pragma unroll
;         for (int b = 0; b < 2; ++b)
; #pragma unroll
;             for (int m = 0; m < 4; ++m)
; #pragma unroll
;                 for (int n = 0; n < 2; ++n) acc[a][b][m][n] = (f32x4){0.f, 0.f, 0.f, 0.f};
;     ...
;         const bool has_next = S.next(ui + 1, nxt);
;         const char* nA = has_next ? (const char*)g.A + (size_t)nxt.pm * tstep : cA; const char* nB = has_next ? (const char*)g.Bt + (size_t)nxt.pn * tstep : cB;
;         for (int t = 0; t < nt; t += 2) {
;             const bool last = (t == nt - 2);
;             const char* a1 = cA + (size_t)(t + 1) * kstep;
;             const char* a2 = last ? nA : cA + (size_t)(t + 2) * kstep; const char* b2 = last ? nB : cB + (size_t)(t + 2) * kstep;
.LBB0_843:
	s_ashr_i32 s37, s36, 31
	s_lshl_b64 s[38:39], s[36:37], 19
	s_add_u32 s38, s29, s38
	s_addc_u32 s39, s31, s39
	s_and_b64 s[40:41], s[6:7], exec
	s_cselect_b32 s9, s39, s11
	s_cselect_b32 s37, s38, s10
	s_ashr_i32 s35, s34, 31
	s_lshl_b64 s[40:41], s[34:35], 19
	s_add_u32 s40, s33, s40
	s_addc_u32 s41, s44, s41
	s_and_b64 s[64:65], s[6:7], exec
	s_cselect_b32 s35, s41, s43
	s_cselect_b32 s63, s40, s42
	s_add_u32 s64, s42, 0x100
	v_mov_b32_e32 v0, 0
	s_addc_u32 s65, s43, 0
	s_mov_b32 s66, -2
	v_mov_b32_e32 v1, v0
	v_mov_b32_e32 v2, v0
	v_mov_b32_e32 v3, v0
	v_mov_b32_e32 v4, v0
	v_mov_b32_e32 v5, v0
	v_mov_b32_e32 v6, v0
	v_mov_b32_e32 v7, v0
	v_mov_b32_e32 v8, v0
	v_mov_b32_e32 v9, v0
	v_mov_b32_e32 v10, v0
	v_mov_b32_e32 v11, v0
	v_mov_b32_e32 v16, v0
	v_mov_b32_e32 v17, v0
	v_mov_b32_e32 v18, v0
	v_mov_b32_e32 v19, v0
	v_mov_b32_e32 v24, v0
	v_mov_b32_e32 v25, v0
	v_mov_b32_e32 v26, v0
	v_mov_b32_e32 v27, v0
	v_mov_b32_e32 v32, v0
	v_mov_b32_e32 v33, v0
	v_mov_b32_e32 v34, v0
	v_mov_b32_e32 v35, v0
	v_mov_b32_e32 v40, v0
	v_mov_b32_e32 v41, v0
	v_mov_b32_e32 v42, v0
	v_mov_b32_e32 v43, v0
	v_mov_b32_e32 v48, v0
	v_mov_b32_e32 v49, v0
	v_mov_b32_e32 v50, v0
	v_mov_b32_e32 v51, v0
	v_mov_b32_e32 v12, v0
	v_mov_b32_e32 v13, v0
	v_mov_b32_e32 v14, v0
	v_mov_b32_e32 v15, v0
	v_mov_b32_e32 v20, v0
	v_mov_b32_e32 v21, v0
	v_mov_b32_e32 v22, v0
	v_mov_b32_e32 v23, v0
	v_mov_b32_e32 v28, v0
	v_mov_b32_e32 v29, v0
	v_mov_b32_e32 v30, v0
	v_mov_b32_e32 v31, v0
	v_mov_b32_e32 v36, v0
	v_mov_b32_e32 v37, v0
	v_mov_b32_e32 v38, v0
	v_mov_b32_e32 v39, v0
	v_mov_b32_e32 v44, v0
	v_mov_b32_e32 v45, v0
	v_mov_b32_e32 v46, v0
	v_mov_b32_e32 v47, v0
	v_mov_b32_e32 v52, v0
	v_mov_b32_e32 v53, v0
	v_mov_b32_e32 v54, v0
	v_mov_b32_e32 v55, v0
	v_mov_b32_e32 v56, v0
	v_mov_b32_e32 v57, v0
	v_mov_b32_e32 v58, v0
	v_mov_b32_e32 v59, v0
	v_mov_b32_e32 v60, v0
	v_mov_b32_e32 v61, v0
	v_mov_b32_e32 v62, v0
	v_mov_b32_e32 v63, v0
	v_mov_b32_e32 v64, v0
	v_mov_b32_e32 v65, v0
	v_mov_b32_e32 v66, v0
	v_mov_b32_e32 v67, v0
	v_mov_b32_e32 v68, v0
	v_mov_b32_e32 v69, v0
	v_mov_b32_e32 v70, v0
	v_mov_b32_e32 v71, v0
	v_mov_b32_e32 v72, v0
	v_mov_b32_e32 v73, v0
	v_mov_b32_e32 v74, v0
	v_mov_b32_e32 v75, v0
	v_mov_b32_e32 v80, v0
	v_mov_b32_e32 v81, v0
	v_mov_b32_e32 v82, v0
	v_mov_b32_e32 v83, v0
	v_mov_b32_e32 v88, v0
	v_mov_b32_e32 v89, v0
	v_mov_b32_e32 v90, v0
	v_mov_b32_e32 v91, v0
	v_mov_b32_e32 v96, v0
	v_mov_b32_e32 v97, v0
	v_mov_b32_e32 v98, v0
	v_mov_b32_e32 v99, v0
	v_mov_b32_e32 v104, v0
	v_mov_b32_e32 v105, v0
	v_mov_b32_e32 v106, v0
	v_mov_b32_e32 v107, v0
	v_mov_b32_e32 v112, v0
	v_mov_b32_e32 v113, v0
	v_mov_b32_e32 v114, v0
	v_mov_b32_e32 v115, v0
	v_mov_b32_e32 v76, v0
	v_mov_b32_e32 v77, v0
	v_mov_b32_e32 v78, v0
	v_mov_b32_e32 v79, v0
	v_mov_b32_e32 v84, v0
	v_mov_b32_e32 v85, v0
	v_mov_b32_e32 v86, v0
	v_mov_b32_e32 v87, v0
	v_mov_b32_e32 v92, v0
	v_mov_b32_e32 v93, v0
	v_mov_b32_e32 v94, v0
	v_mov_b32_e32 v95, v0
	v_mov_b32_e32 v100, v0
	v_mov_b32_e32 v101, v0
	v_mov_b32_e32 v102, v0
	v_mov_b32_e32 v103, v0
	v_mov_b32_e32 v108, v0
	v_mov_b32_e32 v109, v0
	v_mov_b32_e32 v110, v0
	v_mov_b32_e32 v111, v0
	v_mov_b32_e32 v116, v0
	v_mov_b32_e32 v117, v0
	v_mov_b32_e32 v118, v0
	v_mov_b32_e32 v119, v0
	v_mov_b32_e32 v120, v0
	v_mov_b32_e32 v121, v0
	v_mov_b32_e32 v122, v0
	v_mov_b32_e32 v123, v0
	v_mov_b32_e32 v124, v0
	v_mov_b32_e32 v125, v0
	v_mov_b32_e32 v126, v0
	v_mov_b32_e32 v127, v0
	.p2alignl 8, 3212836864

;     __device__ bool next(int i, Unit& u) const { const long L = (long)i * G + c0; if (L >= n) return false; u.pm = (int)L / nN; u.pn = (int)L % nN; return true; }
; template <class Epi, class Sched, bool ALIGN_EPI = false, bool SP2 = false>
; __device__ __forceinline__ void gemm_phase(PG8_LAS unsigned char* lds, const Gemm g, const Sched& S, const Epi& E) {
;     ...
;     f32x4 acc[2][2][4][2];
; #pragma unroll
;     for (int a = 0; a < 2; ++a)
; #pragma unroll
;         for (int b = 0; b < 2; ++b)
; #pragma unroll
;             for (int m = 0; m < 4; ++m)
; #pragma unroll
;                 for (int n = 0; n < 2; ++n) acc[a][b][m][n] = (f32x4){0.f, 0.f, 0.f, 0.f};
;     ...
;         const bool has_next = S.next(ui + 1, nxt);
;         const char* nA = has_next ? (const char*)g.A + (size_t)nxt.pm * tstep : cA; const char* nB = has_next ? (const char*)g.Bt + (size_t)nxt.pn * tstep : cB;
;         for (int t = 0; t < nt; t += 2) {
;             const bool last = (t == nt - 2);
;             const char* a1 = cA + (size_t)(t + 1) * kstep;
;             const char* a2 = last ? nA : cA + (size_t)(t + 2) * kstep; const char* b2 = last ? nB : cB + (size_t)(t + 2) * kstep;
.LBB0_859:
	s_ashr_i32 s29, s28, 31
	s_lshl_b64 s[34:35], s[28:29], 19
	s_add_u32 s34, s33, s34
	s_addc_u32 s35, s50, s35
	s_and_b64 s[38:39], s[36:37], exec
	s_cselect_b32 s29, s35, s45
	s_cselect_b32 s71, s34, s44
	s_ashr_i32 s31, s30, 31
	s_lshl_b64 s[38:39], s[30:31], 19
	s_add_u32 s38, s53, s38
	s_addc_u32 s39, s54, s39
	s_and_b64 s[72:73], s[36:37], exec
	s_cselect_b32 s31, s39, s47
	s_cselect_b32 s72, s38, s46
	s_add_u32 s73, s46, 0x100
	v_mov_b32_e32 v0, 0
	s_addc_u32 s74, s47, 0
	s_mov_b32 s75, -2
	v_mov_b32_e32 v1, v0
	v_mov_b32_e32 v2, v0
	v_mov_b32_e32 v3, v0
	v_mov_b32_e32 v4, v0
	v_mov_b32_e32 v5, v0
	v_mov_b32_e32 v6, v0
	v_mov_b32_e32 v7, v0
	v_mov_b32_e32 v8, v0
	v_mov_b32_e32 v9, v0
	v_mov_b32_e32 v10, v0
	v_mov_b32_e32 v11, v0
	v_mov_b32_e32 v16, v0
	v_mov_b32_e32 v17, v0
	v_mov_b32_e32 v18, v0
	v_mov_b32_e32 v19, v0
	v_mov_b32_e32 v24, v0
	v_mov_b32_e32 v25, v0
	v_mov_b32_e32 v26, v0
	v_mov_b32_e32 v27, v0
	v_mov_b32_e32 v32, v0
	v_mov_b32_e32 v33, v0
	v_mov_b32_e32 v34, v0
	v_mov_b32_e32 v35, v0
	v_mov_b32_e32 v40, v0
	v_mov_b32_e32 v41, v0
	v_mov_b32_e32 v42, v0
	v_mov_b32_e32 v43, v0
	v_mov_b32_e32 v48, v0
	v_mov_b32_e32 v49, v0
	v_mov_b32_e32 v50, v0
	v_mov_b32_e32 v51, v0
	v_mov_b32_e32 v12, v0
	v_mov_b32_e32 v13, v0
	v_mov_b32_e32 v14, v0
	v_mov_b32_e32 v15, v0
	v_mov_b32_e32 v20, v0
	v_mov_b32_e32 v21, v0
	v_mov_b32_e32 v22, v0
	v_mov_b32_e32 v23, v0
	v_mov_b32_e32 v28, v0
	v_mov_b32_e32 v29, v0
	v_mov_b32_e32 v30, v0
	v_mov_b32_e32 v31, v0
	v_mov_b32_e32 v36, v0
	v_mov_b32_e32 v37, v0
	v_mov_b32_e32 v38, v0
	v_mov_b32_e32 v39, v0
	v_mov_b32_e32 v44, v0
	v_mov_b32_e32 v45, v0
	v_mov_b32_e32 v46, v0
	v_mov_b32_e32 v47, v0
	v_mov_b32_e32 v52, v0
	v_mov_b32_e32 v53, v0
	v_mov_b32_e32 v54, v0
	v_mov_b32_e32 v55, v0
	v_mov_b32_e32 v56, v0
	v_mov_b32_e32 v57, v0
	v_mov_b32_e32 v58, v0
	v_mov_b32_e32 v59, v0
	v_mov_b32_e32 v60, v0
	v_mov_b32_e32 v61, v0
	v_mov_b32_e32 v62, v0
	v_mov_b32_e32 v63, v0
	v_mov_b32_e32 v64, v0
	v_mov_b32_e32 v65, v0
	v_mov_b32_e32 v66, v0
	v_mov_b32_e32 v67, v0
	v_mov_b32_e32 v68, v0
	v_mov_b32_e32 v69, v0
	v_mov_b32_e32 v70, v0
	v_mov_b32_e32 v71, v0
	v_mov_b32_e32 v80, v0
	v_mov_b32_e32 v81, v0
	v_mov_b32_e32 v82, v0
	v_mov_b32_e32 v83, v0
	v_mov_b32_e32 v84, v0
	v_mov_b32_e32 v85, v0
	v_mov_b32_e32 v86, v0
	v_mov_b32_e32 v87, v0
	v_mov_b32_e32 v88, v0
	v_mov_b32_e32 v89, v0
	v_mov_b32_e32 v90, v0
	v_mov_b32_e32 v91, v0
	v_mov_b32_e32 v92, v0
	v_mov_b32_e32 v93, v0
	v_mov_b32_e32 v94, v0
	v_mov_b32_e32 v95, v0
	v_mov_b32_e32 v96, v0
	v_mov_b32_e32 v97, v0
	v_mov_b32_e32 v98, v0
	v_mov_b32_e32 v99, v0
	v_mov_b32_e32 v104, v0
	v_mov_b32_e32 v105, v0
	v_mov_b32_e32 v106, v0
	v_mov_b32_e32 v107, v0
	v_mov_b32_e32 v72, v0
	v_mov_b32_e32 v73, v0
	v_mov_b32_e32 v74, v0
	v_mov_b32_e32 v75, v0
	v_mov_b32_e32 v76, v0
	v_mov_b32_e32 v77, v0
	v_mov_b32_e32 v78, v0
	v_mov_b32_e32 v79, v0
	v_mov_b32_e32 v100, v0
	v_mov_b32_e32 v101, v0
	v_mov_b32_e32 v102, v0
	v_mov_b32_e32 v103, v0
	v_mov_b32_e32 v108, v0
	v_mov_b32_e32 v109, v0
	v_mov_b32_e32 v110, v0
	v_mov_b32_e32 v111, v0
	v_mov_b32_e32 v112, v0
	v_mov_b32_e32 v113, v0
	v_mov_b32_e32 v114, v0
	v_mov_b32_e32 v115, v0
	v_mov_b32_e32 v116, v0
	v_mov_b32_e32 v117, v0
	v_mov_b32_e32 v118, v0
	v_mov_b32_e32 v119, v0
	v_mov_b32_e32 v120, v0
	v_mov_b32_e32 v121, v0
	v_mov_b32_e32 v122, v0
	v_mov_b32_e32 v123, v0
	v_mov_b32_e32 v124, v0
	v_mov_b32_e32 v125, v0
	v_mov_b32_e32 v126, v0
	v_mov_b32_e32 v127, v0
	.p2alignl 8, 3212836864

;     __device__ bool next(int i, Unit& u) const { const long L = (long)i * G + c0; if (L >= n) return false; u.pm = (int)L / nN; u.pn = (int)L % nN; return true; }
; template <class Epi, class Sched, bool ALIGN_EPI = false, bool SP2 = false>
; __device__ __forceinline__ void gemm_phase(PG8_LAS unsigned char* lds, const Gemm g, const Sched& S, const Epi& E) {
;     ...
;     f32x4 acc[2][2][4][2];
; #pragma unroll
;     for (int a = 0; a < 2; ++a)
; #pragma unroll
;         for (int b = 0; b < 2; ++b)
; #pragma unroll
;             for (int m = 0; m < 4; ++m)
; #pragma unroll
;                 for (int n = 0; n < 2; ++n) acc[a][b][m][n] = (f32x4){0.f, 0.f, 0.f, 0.f};
;     ...
;         const bool has_next = S.next(ui + 1, nxt);
;         const char* nA = has_next ? (const char*)g.A + (size_t)nxt.pm * tstep : cA; const char* nB = has_next ? (const char*)g.Bt + (size_t)nxt.pn * tstep : cB;
;         for (int t = 0; t < nt; t += 2) {
;             const bool last = (t == nt - 2);
;             const char* a1 = cA + (size_t)(t + 1) * kstep;
;             const char* a2 = last ? nA : cA + (size_t)(t + 2) * kstep; const char* b2 = last ? nB : cB + (size_t)(t + 2) * kstep;
.LBB0_875:
	s_ashr_i32 s31, s30, 31
	s_lshl_b64 s[36:37], s[30:31], 19
	s_add_u32 s36, s52, s36
	s_addc_u32 s37, s53, s37
	s_and_b64 s[40:41], s[38:39], exec
	s_cselect_b32 s31, s37, s47
	s_cselect_b32 s70, s36, s46
	s_ashr_i32 s35, s34, 31
	s_lshl_b64 s[40:41], s[34:35], 19
	s_add_u32 s40, s33, s40
	s_addc_u32 s41, s50, s41
	s_and_b64 s[72:73], s[38:39], exec
	s_cselect_b32 s35, s41, s49
	s_cselect_b32 s71, s40, s48
	s_add_u32 s72, s48, 0x100
	v_mov_b32_e32 v0, 0
	s_addc_u32 s73, s49, 0
	s_mov_b32 s74, -2
	v_mov_b32_e32 v1, v0
	v_mov_b32_e32 v2, v0
	v_mov_b32_e32 v3, v0
	v_mov_b32_e32 v4, v0
	v_mov_b32_e32 v5, v0
	v_mov_b32_e32 v6, v0
	v_mov_b32_e32 v7, v0
	v_mov_b32_e32 v8, v0
	v_mov_b32_e32 v9, v0
	v_mov_b32_e32 v10, v0
	v_mov_b32_e32 v11, v0
	v_mov_b32_e32 v16, v0
	v_mov_b32_e32 v17, v0
	v_mov_b32_e32 v18, v0
	v_mov_b32_e32 v19, v0
	v_mov_b32_e32 v24, v0
	v_mov_b32_e32 v25, v0
	v_mov_b32_e32 v26, v0
	v_mov_b32_e32 v27, v0
	v_mov_b32_e32 v32, v0
	v_mov_b32_e32 v33, v0
	v_mov_b32_e32 v34, v0
	v_mov_b32_e32 v35, v0
	v_mov_b32_e32 v40, v0
	v_mov_b32_e32 v41, v0
	v_mov_b32_e32 v42, v0
	v_mov_b32_e32 v43, v0
	v_mov_b32_e32 v48, v0
	v_mov_b32_e32 v49, v0
	v_mov_b32_e32 v50, v0
	v_mov_b32_e32 v51, v0
	v_mov_b32_e32 v12, v0
	v_mov_b32_e32 v13, v0
	v_mov_b32_e32 v14, v0
	v_mov_b32_e32 v15, v0
	v_mov_b32_e32 v20, v0
	v_mov_b32_e32 v21, v0
	v_mov_b32_e32 v22, v0
	v_mov_b32_e32 v23, v0
	v_mov_b32_e32 v28, v0
	v_mov_b32_e32 v29, v0
	v_mov_b32_e32 v30, v0
	v_mov_b32_e32 v31, v0
	v_mov_b32_e32 v36, v0
	v_mov_b32_e32 v37, v0
	v_mov_b32_e32 v38, v0
	v_mov_b32_e32 v39, v0
	v_mov_b32_e32 v44, v0
	v_mov_b32_e32 v45, v0
	v_mov_b32_e32 v46, v0
	v_mov_b32_e32 v47, v0
	v_mov_b32_e32 v52, v0
	v_mov_b32_e32 v53, v0
	v_mov_b32_e32 v54, v0
	v_mov_b32_e32 v55, v0
	v_mov_b32_e32 v56, v0
	v_mov_b32_e32 v57, v0
	v_mov_b32_e32 v58, v0
	v_mov_b32_e32 v59, v0
	v_mov_b32_e32 v60, v0
	v_mov_b32_e32 v61, v0
	v_mov_b32_e32 v62, v0
	v_mov_b32_e32 v63, v0
	v_mov_b32_e32 v64, v0
	v_mov_b32_e32 v65, v0
	v_mov_b32_e32 v66, v0
	v_mov_b32_e32 v67, v0
	v_mov_b32_e32 v68, v0
	v_mov_b32_e32 v69, v0
	v_mov_b32_e32 v70, v0
	v_mov_b32_e32 v71, v0
	v_mov_b32_e32 v72, v0
	v_mov_b32_e32 v73, v0
	v_mov_b32_e32 v74, v0
	v_mov_b32_e32 v75, v0
	v_mov_b32_e32 v76, v0
	v_mov_b32_e32 v77, v0
	v_mov_b32_e32 v78, v0
	v_mov_b32_e32 v79, v0
	v_mov_b32_e32 v84, v0
	v_mov_b32_e32 v85, v0
	v_mov_b32_e32 v86, v0
	v_mov_b32_e32 v87, v0
	v_mov_b32_e32 v88, v0
	v_mov_b32_e32 v89, v0
	v_mov_b32_e32 v90, v0
	v_mov_b32_e32 v91, v0
	v_mov_b32_e32 v96, v0
	v_mov_b32_e32 v97, v0
	v_mov_b32_e32 v98, v0
	v_mov_b32_e32 v99, v0
	v_mov_b32_e32 v104, v0
	v_mov_b32_e32 v105, v0
	v_mov_b32_e32 v106, v0
	v_mov_b32_e32 v107, v0
	v_mov_b32_e32 v80, v0
	v_mov_b32_e32 v81, v0
	v_mov_b32_e32 v82, v0
	v_mov_b32_e32 v83, v0
	v_mov_b32_e32 v92, v0
	v_mov_b32_e32 v93, v0
	v_mov_b32_e32 v94, v0
	v_mov_b32_e32 v95, v0
	v_mov_b32_e32 v100, v0
	v_mov_b32_e32 v101, v0
	v_mov_b32_e32 v102, v0
	v_mov_b32_e32 v103, v0
	v_mov_b32_e32 v108, v0
	v_mov_b32_e32 v109, v0
	v_mov_b32_e32 v110, v0
	v_mov_b32_e32 v111, v0
	v_mov_b32_e32 v112, v0
	v_mov_b32_e32 v113, v0
	v_mov_b32_e32 v114, v0
	v_mov_b32_e32 v115, v0
	v_mov_b32_e32 v116, v0
	v_mov_b32_e32 v117, v0
	v_mov_b32_e32 v118, v0
	v_mov_b32_e32 v119, v0
	v_mov_b32_e32 v120, v0
	v_mov_b32_e32 v121, v0
	v_mov_b32_e32 v122, v0
	v_mov_b32_e32 v123, v0
	v_mov_b32_e32 v124, v0
	v_mov_b32_e32 v125, v0
	v_mov_b32_e32 v126, v0
	v_mov_b32_e32 v127, v0
	.p2alignl 8, 3212836864

;     __device__ bool next(int i, Unit& u) const { const long L = (long)i * G + c0; if (L >= n) return false; u.pm = (int)L / nN; u.pn = (int)L % nN; return true; }
; template <class Epi, class Sched, bool ALIGN_EPI = false, bool SP2 = false>
; __device__ __forceinline__ void gemm_phase(PG8_LAS unsigned char* lds, const Gemm g, const Sched& S, const Epi& E) {
;     ...
;     f32x4 acc[2][2][4][2];
; #pragma unroll
;     for (int a = 0; a < 2; ++a)
; #pragma unroll
;         for (int b = 0; b < 2; ++b)
; #pragma unroll
;             for (int m = 0; m < 4; ++m)
; #pragma unroll
;                 for (int n = 0; n < 2; ++n) acc[a][b][m][n] = (f32x4){0.f, 0.f, 0.f, 0.f};
;     ...
;         const bool has_next = S.next(ui + 1, nxt);
;         const char* nA = has_next ? (const char*)g.A + (size_t)nxt.pm * tstep : cA; const char* nB = has_next ? (const char*)g.Bt + (size_t)nxt.pn * tstep : cB;
;         for (int t = 0; t < nt; t += 2) {
;             const bool last = (t == nt - 2);
;             const char* a1 = cA + (size_t)(t + 1) * kstep;
;             const char* a2 = last ? nA : cA + (size_t)(t + 2) * kstep; const char* b2 = last ? nB : cB + (size_t)(t + 2) * kstep;
.LBB0_1374:
	s_ashr_i32 s29, s28, 31
	s_lshl_b64 s[30:31], s[28:29], 19
	s_add_u32 s30, s42, s30
	s_addc_u32 s31, s43, s31
	s_and_b64 s[34:35], s[6:7], exec
	s_cselect_b32 s29, s31, s41
	s_cselect_b32 s37, s30, s40
	s_ashr_i32 s27, s26, 31
	s_lshl_b64 s[34:35], s[26:27], 19
	s_add_u32 s34, s44, s34
	s_addc_u32 s35, s45, s35
	s_and_b64 s[62:63], s[6:7], exec
	s_cselect_b32 s27, s35, s39
	s_cselect_b32 s61, s34, s38
	s_add_u32 s62, s38, 0x100
	s_addc_u32 s63, s39, 0
	s_add_u32 s38, s40, 0x40080
	v_mov_b32_e32 v0, 0
	s_addc_u32 s39, s41, 0
	s_mov_b32 s40, -2
	s_waitcnt lgkmcnt(0)
	v_mov_b32_e32 v1, v0
	v_mov_b32_e32 v2, v0
	v_mov_b32_e32 v3, v0
	v_mov_b32_e32 v4, v0
	v_mov_b32_e32 v5, v0
	v_mov_b32_e32 v6, v0
	v_mov_b32_e32 v7, v0
	v_mov_b32_e32 v16, v0
	v_mov_b32_e32 v17, v0
	v_mov_b32_e32 v18, v0
	v_mov_b32_e32 v19, v0
	v_mov_b32_e32 v20, v0
	v_mov_b32_e32 v21, v0
	v_mov_b32_e32 v22, v0
	v_mov_b32_e32 v23, v0
	v_mov_b32_e32 v32, v0
	v_mov_b32_e32 v33, v0
	v_mov_b32_e32 v34, v0
	v_mov_b32_e32 v35, v0
	v_mov_b32_e32 v36, v0
	v_mov_b32_e32 v37, v0
	v_mov_b32_e32 v38, v0
	v_mov_b32_e32 v39, v0
	v_mov_b32_e32 v48, v0
	v_mov_b32_e32 v49, v0
	v_mov_b32_e32 v50, v0
	v_mov_b32_e32 v51, v0
	v_mov_b32_e32 v52, v0
	v_mov_b32_e32 v53, v0
	v_mov_b32_e32 v54, v0
	v_mov_b32_e32 v55, v0
	v_mov_b32_e32 v8, v0
	v_mov_b32_e32 v9, v0
	v_mov_b32_e32 v10, v0
	v_mov_b32_e32 v11, v0
	v_mov_b32_e32 v12, v0
	v_mov_b32_e32 v13, v0
	v_mov_b32_e32 v14, v0
	v_mov_b32_e32 v15, v0
	v_mov_b32_e32 v24, v0
	v_mov_b32_e32 v25, v0
	v_mov_b32_e32 v26, v0
	v_mov_b32_e32 v27, v0
	v_mov_b32_e32 v28, v0
	v_mov_b32_e32 v29, v0
	v_mov_b32_e32 v30, v0
	v_mov_b32_e32 v31, v0
	v_mov_b32_e32 v40, v0
	v_mov_b32_e32 v41, v0
	v_mov_b32_e32 v42, v0
	v_mov_b32_e32 v43, v0
	v_mov_b32_e32 v44, v0
	v_mov_b32_e32 v45, v0
	v_mov_b32_e32 v46, v0
	v_mov_b32_e32 v47, v0
	v_mov_b32_e32 v56, v0
	v_mov_b32_e32 v57, v0
	v_mov_b32_e32 v58, v0
	v_mov_b32_e32 v59, v0
	v_mov_b32_e32 v60, v0
	v_mov_b32_e32 v61, v0
	v_mov_b32_e32 v62, v0
	v_mov_b32_e32 v63, v0
	v_mov_b32_e32 v64, v0
	v_mov_b32_e32 v65, v0
	v_mov_b32_e32 v66, v0
	v_mov_b32_e32 v67, v0
	v_mov_b32_e32 v68, v0
	v_mov_b32_e32 v69, v0
	v_mov_b32_e32 v70, v0
	v_mov_b32_e32 v71, v0
	v_mov_b32_e32 v80, v0
	v_mov_b32_e32 v81, v0
	v_mov_b32_e32 v82, v0
	v_mov_b32_e32 v83, v0
	v_mov_b32_e32 v84, v0
	v_mov_b32_e32 v85, v0
	v_mov_b32_e32 v86, v0
	v_mov_b32_e32 v87, v0
	v_mov_b32_e32 v96, v0
	v_mov_b32_e32 v97, v0
	v_mov_b32_e32 v98, v0
	v_mov_b32_e32 v99, v0
	v_mov_b32_e32 v100, v0
	v_mov_b32_e32 v101, v0
	v_mov_b32_e32 v102, v0
	v_mov_b32_e32 v103, v0
	v_mov_b32_e32 v112, v0
	v_mov_b32_e32 v113, v0
	v_mov_b32_e32 v114, v0
	v_mov_b32_e32 v115, v0
	v_mov_b32_e32 v116, v0
	v_mov_b32_e32 v117, v0
	v_mov_b32_e32 v118, v0
	v_mov_b32_e32 v119, v0
	v_mov_b32_e32 v72, v0
	v_mov_b32_e32 v73, v0
	v_mov_b32_e32 v74, v0
	v_mov_b32_e32 v75, v0
	v_mov_b32_e32 v76, v0
	v_mov_b32_e32 v77, v0
	v_mov_b32_e32 v78, v0
	v_mov_b32_e32 v79, v0
	v_mov_b32_e32 v88, v0
	v_mov_b32_e32 v89, v0
	v_mov_b32_e32 v90, v0
	v_mov_b32_e32 v91, v0
	v_mov_b32_e32 v92, v0
	v_mov_b32_e32 v93, v0
	v_mov_b32_e32 v94, v0
	v_mov_b32_e32 v95, v0
	v_mov_b32_e32 v104, v0
	v_mov_b32_e32 v105, v0
	v_mov_b32_e32 v106, v0
	v_mov_b32_e32 v107, v0
	v_mov_b32_e32 v108, v0
	v_mov_b32_e32 v109, v0
	v_mov_b32_e32 v110, v0
	v_mov_b32_e32 v111, v0
	v_mov_b32_e32 v120, v0
	v_mov_b32_e32 v121, v0
	v_mov_b32_e32 v122, v0
	v_mov_b32_e32 v123, v0
	v_mov_b32_e32 v124, v0
	v_mov_b32_e32 v125, v0
	v_mov_b32_e32 v126, v0
	v_mov_b32_e32 v127, v0
	.p2alignl 8, 3212836864

;     __device__ bool next(int i, Unit& u) const { const long L = (long)i * G + c0; if (L >= n) return false; u.pm = (int)L / nN; u.pn = (int)L % nN; return true; }
; template <class Epi, class Sched, bool ALIGN_EPI = false, bool SP2 = false>
; __device__ __forceinline__ void gemm_phase(PG8_LAS unsigned char* lds, const Gemm g, const Sched& S, const Epi& E) {
;     ...
;         const bool has_next = S.next(ui + 1, nxt);
;         const char* nA = has_next ? (const char*)g.A + (size_t)nxt.pm * tstep : cA; const char* nB = has_next ? (const char*)g.Bt + (size_t)nxt.pn * tstep : cB;
;         for (int t = 0; t < nt; t += 2) {
;             const bool last = (t == nt - 2);
;             const char* a1 = cA + (size_t)(t + 1) * kstep;
;             const char* a2 = last ? nA : cA + (size_t)(t + 2) * kstep; const char* b2 = last ? nB : cB + (size_t)(t + 2) * kstep;
;             const char* a3 = a2 + kstep; const char* b3 = b2 + kstep;
;     ...
; #pragma unroll
;         for (int a = 0; a < 2; ++a)
; #pragma unroll
;             for (int b = 0; b < 2; ++b)
; #pragma unroll
;                 for (int m = 0; m < 4; ++m)
; #pragma unroll
;                     for (int n = 0; n < 2; ++n) acc[a][b][m][n] = (f32x4){0.f, 0.f, 0.f, 0.f};
;         cur = nxt; cA = nA; cB = nB; ++ui;
.LBB0_1458:
	s_ashr_i32 s37, s36, 31
	s_lshl_b64 s[38:39], s[36:37], 19
	s_add_u32 s38, s31, s38
	s_addc_u32 s39, s44, s39
	s_and_b64 s[40:41], s[6:7], exec
	s_cselect_b32 s9, s39, s11
	s_cselect_b32 s37, s38, s10
	s_ashr_i32 s35, s34, 31
	s_lshl_b64 s[40:41], s[34:35], 19
	s_add_u32 s40, s45, s40
	s_addc_u32 s41, s46, s41
	s_and_b64 s[62:63], s[6:7], exec
	s_cselect_b32 s35, s41, s43
	s_cselect_b32 s62, s40, s42
	s_add_u32 s63, s42, 0x100
	v_mov_b32_e32 v0, 0
	s_addc_u32 s64, s43, 0
	s_mov_b32 s65, -2
	v_mov_b32_e32 v1, v0
	v_mov_b32_e32 v2, v0
	v_mov_b32_e32 v3, v0
	v_mov_b32_e32 v4, v0
	v_mov_b32_e32 v5, v0
	v_mov_b32_e32 v6, v0
	v_mov_b32_e32 v7, v0
	v_mov_b32_e32 v8, v0
	v_mov_b32_e32 v9, v0
	v_mov_b32_e32 v10, v0
	v_mov_b32_e32 v11, v0
	v_mov_b32_e32 v16, v0
	v_mov_b32_e32 v17, v0
	v_mov_b32_e32 v18, v0
	v_mov_b32_e32 v19, v0
	v_mov_b32_e32 v24, v0
	v_mov_b32_e32 v25, v0
	v_mov_b32_e32 v26, v0
	v_mov_b32_e32 v27, v0
	v_mov_b32_e32 v32, v0
	v_mov_b32_e32 v33, v0
	v_mov_b32_e32 v34, v0
	v_mov_b32_e32 v35, v0
	v_mov_b32_e32 v40, v0
	v_mov_b32_e32 v41, v0
	v_mov_b32_e32 v42, v0
	v_mov_b32_e32 v43, v0
	v_mov_b32_e32 v48, v0
	v_mov_b32_e32 v49, v0
	v_mov_b32_e32 v50, v0
	v_mov_b32_e32 v51, v0
	v_mov_b32_e32 v12, v0
	v_mov_b32_e32 v13, v0
	v_mov_b32_e32 v14, v0
	v_mov_b32_e32 v15, v0
	v_mov_b32_e32 v20, v0
	v_mov_b32_e32 v21, v0
	v_mov_b32_e32 v22, v0
	v_mov_b32_e32 v23, v0
	v_mov_b32_e32 v28, v0
	v_mov_b32_e32 v29, v0
	v_mov_b32_e32 v30, v0
	v_mov_b32_e32 v31, v0
	v_mov_b32_e32 v36, v0
	v_mov_b32_e32 v37, v0
	v_mov_b32_e32 v38, v0
	v_mov_b32_e32 v39, v0
	v_mov_b32_e32 v44, v0
	v_mov_b32_e32 v45, v0
	v_mov_b32_e32 v46, v0
	v_mov_b32_e32 v47, v0
	v_mov_b32_e32 v52, v0
	v_mov_b32_e32 v53, v0
	v_mov_b32_e32 v54, v0
	v_mov_b32_e32 v55, v0
	v_mov_b32_e32 v56, v0
	v_mov_b32_e32 v57, v0
	v_mov_b32_e32 v58, v0
	v_mov_b32_e32 v59, v0
	v_mov_b32_e32 v60, v0
	v_mov_b32_e32 v61, v0
	v_mov_b32_e32 v62, v0
	v_mov_b32_e32 v63, v0
	v_mov_b32_e32 v64, v0
	v_mov_b32_e32 v65, v0
	v_mov_b32_e32 v66, v0
	v_mov_b32_e32 v67, v0
	v_mov_b32_e32 v68, v0
	v_mov_b32_e32 v69, v0
	v_mov_b32_e32 v70, v0
	v_mov_b32_e32 v71, v0
	v_mov_b32_e32 v72, v0
	v_mov_b32_e32 v73, v0
	v_mov_b32_e32 v74, v0
	v_mov_b32_e32 v75, v0
	v_mov_b32_e32 v80, v0
	v_mov_b32_e32 v81, v0
	v_mov_b32_e32 v82, v0
	v_mov_b32_e32 v83, v0
	v_mov_b32_e32 v88, v0
	v_mov_b32_e32 v89, v0
	v_mov_b32_e32 v90, v0
	v_mov_b32_e32 v91, v0
	v_mov_b32_e32 v96, v0
	v_mov_b32_e32 v97, v0
	v_mov_b32_e32 v98, v0
	v_mov_b32_e32 v99, v0
	v_mov_b32_e32 v104, v0
	v_mov_b32_e32 v105, v0
	v_mov_b32_e32 v106, v0
	v_mov_b32_e32 v107, v0
	v_mov_b32_e32 v112, v0
	v_mov_b32_e32 v113, v0
	v_mov_b32_e32 v114, v0
	v_mov_b32_e32 v115, v0
	v_mov_b32_e32 v76, v0
	v_mov_b32_e32 v77, v0
	v_mov_b32_e32 v78, v0
	v_mov_b32_e32 v79, v0
	v_mov_b32_e32 v84, v0
	v_mov_b32_e32 v85, v0
	v_mov_b32_e32 v86, v0
	v_mov_b32_e32 v87, v0
	v_mov_b32_e32 v92, v0
	v_mov_b32_e32 v93, v0
	v_mov_b32_e32 v94, v0
	v_mov_b32_e32 v95, v0
	v_mov_b32_e32 v100, v0
	v_mov_b32_e32 v101, v0
	v_mov_b32_e32 v102, v0
	v_mov_b32_e32 v103, v0
	v_mov_b32_e32 v108, v0
	v_mov_b32_e32 v109, v0
	v_mov_b32_e32 v110, v0
	v_mov_b32_e32 v111, v0
	v_mov_b32_e32 v116, v0
	v_mov_b32_e32 v117, v0
	v_mov_b32_e32 v118, v0
	v_mov_b32_e32 v119, v0
	v_mov_b32_e32 v120, v0
	v_mov_b32_e32 v121, v0
	v_mov_b32_e32 v122, v0
	v_mov_b32_e32 v123, v0
	v_mov_b32_e32 v124, v0
	v_mov_b32_e32 v125, v0
	v_mov_b32_e32 v126, v0
	v_mov_b32_e32 v127, v0
	.p2alignl 8, 3212836864

;     __device__ bool next(int i, Unit& u) const { const long L = (long)i * G + c0; if (L >= n) return false; u.pm = (int)L / nN; u.pn = (int)L % nN; return true; }
; template <class Epi, class Sched, bool ALIGN_EPI = false, bool SP2 = false>
; __device__ __forceinline__ void gemm_phase(PG8_LAS unsigned char* lds, const Gemm g, const Sched& S, const Epi& E) {
;     ...
;         const bool has_next = S.next(ui + 1, nxt);
;         const char* nA = has_next ? (const char*)g.A + (size_t)nxt.pm * tstep : cA; const char* nB = has_next ? (const char*)g.Bt + (size_t)nxt.pn * tstep : cB;
;         for (int t = 0; t < nt; t += 2) {
;             const bool last = (t == nt - 2);
;             const char* a1 = cA + (size_t)(t + 1) * kstep;
;             const char* a2 = last ? nA : cA + (size_t)(t + 2) * kstep; const char* b2 = last ? nB : cB + (size_t)(t + 2) * kstep;
;             const char* a3 = a2 + kstep; const char* b3 = b2 + kstep;
;     ...
; #pragma unroll
;         for (int a = 0; a < 2; ++a)
; #pragma unroll
;             for (int b = 0; b < 2; ++b)
; #pragma unroll
;                 for (int m = 0; m < 4; ++m)
; #pragma unroll
;                     for (int n = 0; n < 2; ++n) acc[a][b][m][n] = (f32x4){0.f, 0.f, 0.f, 0.f};
;         cur = nxt; cA = nA; cB = nB; ++ui;
.LBB0_1657:
	s_ashr_i32 s37, s36, 31
	s_lshl_b64 s[38:39], s[36:37], 19
	s_add_u32 s38, s29, s38
	s_addc_u32 s39, s31, s39
	s_and_b64 s[40:41], s[6:7], exec
	s_cselect_b32 s9, s39, s11
	s_cselect_b32 s37, s38, s10
	s_ashr_i32 s35, s34, 31
	s_lshl_b64 s[40:41], s[34:35], 19
	s_add_u32 s40, s44, s40
	s_addc_u32 s41, s45, s41
	s_and_b64 s[64:65], s[6:7], exec
	s_cselect_b32 s35, s41, s43
	s_cselect_b32 s64, s40, s42
	s_add_u32 s65, s42, 0x100
	v_mov_b32_e32 v0, 0
	s_addc_u32 s66, s43, 0
	s_mov_b32 s67, -2
	v_mov_b32_e32 v1, v0
	v_mov_b32_e32 v2, v0
	v_mov_b32_e32 v3, v0
	v_mov_b32_e32 v4, v0
	v_mov_b32_e32 v5, v0
	v_mov_b32_e32 v6, v0
	v_mov_b32_e32 v7, v0
	v_mov_b32_e32 v16, v0
	v_mov_b32_e32 v17, v0
	v_mov_b32_e32 v18, v0
	v_mov_b32_e32 v19, v0
	v_mov_b32_e32 v20, v0
	v_mov_b32_e32 v21, v0
	v_mov_b32_e32 v22, v0
	v_mov_b32_e32 v23, v0
	v_mov_b32_e32 v32, v0
	v_mov_b32_e32 v33, v0
	v_mov_b32_e32 v34, v0
	v_mov_b32_e32 v35, v0
	v_mov_b32_e32 v36, v0
	v_mov_b32_e32 v37, v0
	v_mov_b32_e32 v38, v0
	v_mov_b32_e32 v39, v0
	v_mov_b32_e32 v48, v0
	v_mov_b32_e32 v49, v0
	v_mov_b32_e32 v50, v0
	v_mov_b32_e32 v51, v0
	v_mov_b32_e32 v52, v0
	v_mov_b32_e32 v53, v0
	v_mov_b32_e32 v54, v0
	v_mov_b32_e32 v55, v0
	v_mov_b32_e32 v8, v0
	v_mov_b32_e32 v9, v0
	v_mov_b32_e32 v10, v0
	v_mov_b32_e32 v11, v0
	v_mov_b32_e32 v12, v0
	v_mov_b32_e32 v13, v0
	v_mov_b32_e32 v14, v0
	v_mov_b32_e32 v15, v0
	v_mov_b32_e32 v24, v0
	v_mov_b32_e32 v25, v0
	v_mov_b32_e32 v26, v0
	v_mov_b32_e32 v27, v0
	v_mov_b32_e32 v28, v0
	v_mov_b32_e32 v29, v0
	v_mov_b32_e32 v30, v0
	v_mov_b32_e32 v31, v0
	v_mov_b32_e32 v40, v0
	v_mov_b32_e32 v41, v0
	v_mov_b32_e32 v42, v0
	v_mov_b32_e32 v43, v0
	v_mov_b32_e32 v44, v0
	v_mov_b32_e32 v45, v0
	v_mov_b32_e32 v46, v0
	v_mov_b32_e32 v47, v0
	v_mov_b32_e32 v56, v0
	v_mov_b32_e32 v57, v0
	v_mov_b32_e32 v58, v0
	v_mov_b32_e32 v59, v0
	v_mov_b32_e32 v60, v0
	v_mov_b32_e32 v61, v0
	v_mov_b32_e32 v62, v0
	v_mov_b32_e32 v63, v0
	v_mov_b32_e32 v64, v0
	v_mov_b32_e32 v65, v0
	v_mov_b32_e32 v66, v0
	v_mov_b32_e32 v67, v0
	v_mov_b32_e32 v68, v0
	v_mov_b32_e32 v69, v0
	v_mov_b32_e32 v70, v0
	v_mov_b32_e32 v71, v0
	v_mov_b32_e32 v80, v0
	v_mov_b32_e32 v81, v0
	v_mov_b32_e32 v82, v0
	v_mov_b32_e32 v83, v0
	v_mov_b32_e32 v84, v0
	v_mov_b32_e32 v85, v0
	v_mov_b32_e32 v86, v0
	v_mov_b32_e32 v87, v0
	v_mov_b32_e32 v96, v0
	v_mov_b32_e32 v97, v0
	v_mov_b32_e32 v98, v0
	v_mov_b32_e32 v99, v0
	v_mov_b32_e32 v100, v0
	v_mov_b32_e32 v101, v0
	v_mov_b32_e32 v102, v0
	v_mov_b32_e32 v103, v0
	v_mov_b32_e32 v112, v0
	v_mov_b32_e32 v113, v0
	v_mov_b32_e32 v114, v0
	v_mov_b32_e32 v115, v0
	v_mov_b32_e32 v116, v0
	v_mov_b32_e32 v117, v0
	v_mov_b32_e32 v118, v0
	v_mov_b32_e32 v119, v0
	v_mov_b32_e32 v72, v0
	v_mov_b32_e32 v73, v0
	v_mov_b32_e32 v74, v0
	v_mov_b32_e32 v75, v0
	v_mov_b32_e32 v76, v0
	v_mov_b32_e32 v77, v0
	v_mov_b32_e32 v78, v0
	v_mov_b32_e32 v79, v0
	v_mov_b32_e32 v88, v0
	v_mov_b32_e32 v89, v0
	v_mov_b32_e32 v90, v0
	v_mov_b32_e32 v91, v0
	v_mov_b32_e32 v92, v0
	v_mov_b32_e32 v93, v0
	v_mov_b32_e32 v94, v0
	v_mov_b32_e32 v95, v0
	v_mov_b32_e32 v104, v0
	v_mov_b32_e32 v105, v0
	v_mov_b32_e32 v106, v0
	v_mov_b32_e32 v107, v0
	v_mov_b32_e32 v108, v0
	v_mov_b32_e32 v109, v0
	v_mov_b32_e32 v110, v0
	v_mov_b32_e32 v111, v0
	v_mov_b32_e32 v120, v0
	v_mov_b32_e32 v121, v0
	v_mov_b32_e32 v122, v0
	v_mov_b32_e32 v123, v0
	v_mov_b32_e32 v124, v0
	v_mov_b32_e32 v125, v0
	v_mov_b32_e32 v126, v0
	v_mov_b32_e32 v127, v0
	.p2alignl 8, 3212836864

; template <class Epi, class Sched, bool ALIGN_EPI = false, bool SP2 = false>
; __device__ __forceinline__ void gemm_phase(PG8_LAS unsigned char* lds, const Gemm g, const Sched& S, const Epi& E) {
;     ...
;         for (int t = 0; t < nt; t += 2) {
;             const bool last = (t == nt - 2);
;             const char* a1 = cA + (size_t)(t + 1) * kstep;
;             const char* a2 = last ? nA : cA + (size_t)(t + 2) * kstep; const char* b2 = last ? nB : cB + (size_t)(t + 2) * kstep;
;             const char* a3 = a2 + kstep; const char* b3 = b2 + kstep;
;     ...
; #pragma unroll
;         for (int a = 0; a < 2; ++a)
; #pragma unroll
;             for (int b = 0; b < 2; ++b)
; #pragma unroll
;                 for (int m = 0; m < 4; ++m)
; #pragma unroll
;                     for (int n = 0; n < 2; ++n) acc[a][b][m][n] = (f32x4){0.f, 0.f, 0.f, 0.f};
;         cur = nxt; cA = nA; cB = nB; ++ui;
.LBB0_1731:
	s_add_u32 s58, s30, 0x100
	s_addc_u32 s59, s31, 0
	s_add_u32 s30, s34, 0xb0080
	v_mov_b32_e32 v0, 0
	s_addc_u32 s31, s35, 0
	s_mov_b32 s34, -2
	s_waitcnt lgkmcnt(0)
	v_mov_b32_e32 v1, v0
	v_mov_b32_e32 v2, v0
	v_mov_b32_e32 v3, v0
	v_mov_b32_e32 v4, v0
	v_mov_b32_e32 v5, v0
	v_mov_b32_e32 v6, v0
	v_mov_b32_e32 v7, v0
	v_mov_b32_e32 v16, v0
	v_mov_b32_e32 v17, v0
	v_mov_b32_e32 v18, v0
	v_mov_b32_e32 v19, v0
	v_mov_b32_e32 v20, v0
	v_mov_b32_e32 v21, v0
	v_mov_b32_e32 v22, v0
	v_mov_b32_e32 v23, v0
	v_mov_b32_e32 v32, v0
	v_mov_b32_e32 v33, v0
	v_mov_b32_e32 v34, v0
	v_mov_b32_e32 v35, v0
	v_mov_b32_e32 v36, v0
	v_mov_b32_e32 v37, v0
	v_mov_b32_e32 v38, v0
	v_mov_b32_e32 v39, v0
	v_mov_b32_e32 v48, v0
	v_mov_b32_e32 v49, v0
	v_mov_b32_e32 v50, v0
	v_mov_b32_e32 v51, v0
	v_mov_b32_e32 v52, v0
	v_mov_b32_e32 v53, v0
	v_mov_b32_e32 v54, v0
	v_mov_b32_e32 v55, v0
	v_mov_b32_e32 v8, v0
	v_mov_b32_e32 v9, v0
	v_mov_b32_e32 v10, v0
	v_mov_b32_e32 v11, v0
	v_mov_b32_e32 v12, v0
	v_mov_b32_e32 v13, v0
	v_mov_b32_e32 v14, v0
	v_mov_b32_e32 v15, v0
	v_mov_b32_e32 v24, v0
	v_mov_b32_e32 v25, v0
	v_mov_b32_e32 v26, v0
	v_mov_b32_e32 v27, v0
	v_mov_b32_e32 v28, v0
	v_mov_b32_e32 v29, v0
	v_mov_b32_e32 v30, v0
	v_mov_b32_e32 v31, v0
	v_mov_b32_e32 v40, v0
	v_mov_b32_e32 v41, v0
	v_mov_b32_e32 v42, v0
	v_mov_b32_e32 v43, v0
	v_mov_b32_e32 v44, v0
	v_mov_b32_e32 v45, v0
	v_mov_b32_e32 v46, v0
	v_mov_b32_e32 v47, v0
	v_mov_b32_e32 v56, v0
	v_mov_b32_e32 v57, v0
	v_mov_b32_e32 v58, v0
	v_mov_b32_e32 v59, v0
	v_mov_b32_e32 v60, v0
	v_mov_b32_e32 v61, v0
	v_mov_b32_e32 v62, v0
	v_mov_b32_e32 v63, v0
	v_mov_b32_e32 v64, v0
	v_mov_b32_e32 v65, v0
	v_mov_b32_e32 v66, v0
	v_mov_b32_e32 v67, v0
	v_mov_b32_e32 v68, v0
	v_mov_b32_e32 v69, v0
	v_mov_b32_e32 v70, v0
	v_mov_b32_e32 v71, v0
	v_mov_b32_e32 v80, v0
	v_mov_b32_e32 v81, v0
	v_mov_b32_e32 v82, v0
	v_mov_b32_e32 v83, v0
	v_mov_b32_e32 v84, v0
	v_mov_b32_e32 v85, v0
	v_mov_b32_e32 v86, v0
	v_mov_b32_e32 v87, v0
	v_mov_b32_e32 v96, v0
	v_mov_b32_e32 v97, v0
	v_mov_b32_e32 v98, v0
	v_mov_b32_e32 v99, v0
	v_mov_b32_e32 v100, v0
	v_mov_b32_e32 v101, v0
	v_mov_b32_e32 v102, v0
	v_mov_b32_e32 v103, v0
	v_mov_b32_e32 v112, v0
	v_mov_b32_e32 v113, v0
	v_mov_b32_e32 v114, v0
	v_mov_b32_e32 v115, v0
	v_mov_b32_e32 v116, v0
	v_mov_b32_e32 v117, v0
	v_mov_b32_e32 v118, v0
	v_mov_b32_e32 v119, v0
	v_mov_b32_e32 v72, v0
	v_mov_b32_e32 v73, v0
	v_mov_b32_e32 v74, v0
	v_mov_b32_e32 v75, v0
	v_mov_b32_e32 v76, v0
	v_mov_b32_e32 v77, v0
	v_mov_b32_e32 v78, v0
	v_mov_b32_e32 v79, v0
	v_mov_b32_e32 v88, v0
	v_mov_b32_e32 v89, v0
	v_mov_b32_e32 v90, v0
	v_mov_b32_e32 v91, v0
	v_mov_b32_e32 v92, v0
	v_mov_b32_e32 v93, v0
	v_mov_b32_e32 v94, v0
	v_mov_b32_e32 v95, v0
	v_mov_b32_e32 v104, v0
	v_mov_b32_e32 v105, v0
	v_mov_b32_e32 v106, v0
	v_mov_b32_e32 v107, v0
	v_mov_b32_e32 v108, v0
	v_mov_b32_e32 v109, v0
	v_mov_b32_e32 v110, v0
	v_mov_b32_e32 v111, v0
	v_mov_b32_e32 v120, v0
	v_mov_b32_e32 v121, v0
	v_mov_b32_e32 v122, v0
	v_mov_b32_e32 v123, v0
	v_mov_b32_e32 v124, v0
	v_mov_b32_e32 v125, v0
	v_mov_b32_e32 v126, v0
	v_mov_b32_e32 v127, v0
	.p2alignl 8, 3212836864
